# added grid-size guard: transposes schedule over idle workgroups only with a 256-workgroup grid, otherwise all transposes run in the prologue
# speedup vs baseline: 1.0117x; 1.0117x over previous
; __device__ __forceinline__ int bid_() { int t = blockIdx.x; asm volatile("" : "+s"(t)); return t; }
; __device__ __forceinline__ void prologue_phase(const Params& P, float* L) {
;     ...
;     bf16* W13 = (bf16*)(ws + WS_W13); bf16* W2 = (bf16*)(ws + WS_W2); bf16* WIN = (bf16*)(ws + WS_WIN); bf16* WOUT = (bf16*)(ws + WS_WOUT);
;     float* scr = L + wave * (64 * 65);
;     const int gw = bid_() * 8 + wave, NGW = gridDim.x * 8;
;     constexpr int I_F = 2816, I_LF = 3 * I_F, I_FFN = 4 * I_LF, I_IN = 32 * 101, I_OUT = 32 * 32, I_ALL = I_FFN + 2 * I_IN + 2 * I_OUT;
;     for (int it = gw; it < I_ALL; it += NGW) {
.LBB0_379:
	s_lshl_b32 s18, s2, 3
	v_readfirstlane_b32 s0, v168
	s_lshr_b32 s0, s0, 6
	s_add_u32 s18, s18, s0
	s_load_dword s20, s[38:39], 0x0
	s_mov_b32 s19, 6552
	s_mov_b32 s98, 5632
	s_mov_b32 s99, 0
	s_mov_b32 s100, 0xb00
	s_waitcnt lgkmcnt(0)
	s_cmp_eq_u32 s20, 0x100
	s_cselect_b32 s19, s19, 0xa540
	s_cselect_b32 s98, s98, 0x7fffffff
	s_cselect_b32 s99, s99, 0
	s_cselect_b32 s100, s100, 0
	s_lshl_b32 s20, s20, 3

; __device__ __forceinline__ int bid_() { int t = blockIdx.x; asm volatile("" : "+s"(t)); return t; }
; __device__ __forceinline__ void prologue_phase(const Params& P, float* L) {
;     ...
;     const int gw = bid_() * 8 + wave, NGW = gridDim.x * 8;
;     constexpr int I_F = 2816, I_LF = 3 * I_F, I_FFN = 4 * I_LF, I_IN = 32 * 101, I_OUT = 32 * 32, I_ALL = I_FFN + 2 * I_IN + 2 * I_OUT;
;     for (int it = gw; it < I_ALL; it += NGW) {
.Lhk_go:
	s_load_dword s21, s[38:39], 0x0
	s_waitcnt lgkmcnt(0)
	s_cmp_eq_u32 s21, 0x100
	s_cbranch_scc0 .Lhk_resume
	s_barrier
	v_readfirstlane_b32 s21, v168
	s_lshr_b32 s21, s21, 6
	s_cmp_ge_u32 s21, s3
	s_cbranch_scc1 .Lhk_resume
	s_sub_u32 s18, s2, s0
	s_mul_i32 s18, s18, s3
	s_add_u32 s18, s18, s21
	s_mul_i32 s20, s1, s3
	s_branch .Ltr_entry
